# v39 + next-unit decode/preheader hoisted into the EpiUp epilogue (SALU in the VALU shadow)
# speedup vs baseline: 1.0070x; 1.0023x over previous
; #define PG8_STAGE(bufoff, gbase, voff) do { _Pragma("unroll") for (int _i = 0; _i < 2; ++_i) glds16_s((gbase), (voff)[_i], ldsb + (unsigned)((bufoff) + _i * 8192)); } while (0)
;     __device__ bool next(int i, Unit& u) const {
;         const long L = (long)i * G + c; if (L >= nwg) return false;
;         int wgid = (int)L; { const int q = nwg / NXCD, r = nwg % NXCD, xcd = wgid % NXCD, off = wgid / NXCD; wgid = (xcd < r ? xcd * (q + 1) : r * (q + 1) + (xcd - r) * q) + off; }
;         const int nig = WGM * nN, gid = wgid / nig, fm = gid * WGM, gsz = (nM - fm) < WGM ? (nM - fm) : WGM;
;         u.pm = fm + ((wgid % nig) % gsz); u.pn = (wgid % nig) / gsz; u.g = 0; u.part = 0; u.keep = 0; return true;
;     }
; template <class Prob, class Epi, bool I8 = false, bool ALIGN_EPI = true, bool SP2 = true>
; __device__ __forceinline__ void gemm_phase(LAS unsigned char* lds, int wave, const Prob& P, const Epi& E) {
;     ...
;     for (int i = 0; i < 2; ++i) { int R, C; stage_rc(tid * 16 + i * 8192, R, C); const int Rb = (R & ~31) + perm32(R & 31);
;         voffA[i] = P.a_rowoff(R) + (unsigned)C * 2u; voffB[i] = P.b_rowoff(Rb) + (unsigned)C * 2u; }
;     const size_t kstep = (size_t)(BK * 2);
;     const size_t hstepA = P.a_hstep(), hstepB = P.b_hstep();
;     const unsigned ldsw = (unsigned)wid * 1024u;
;     const unsigned ldsb = (unsigned)(size_t)lds + ldsw;
;     const int aoff = lds_byte(wr * 64 + fr, fq * 8), boff = lds_byte(wc * 32 + fr, fq * 8);
;     ...
;     Unit cur, nxt; int ui = 0;
;     if (!P.next(0, cur)) return;
;     Acc acc;
; #pragma unroll
;     for (int a = 0; a < 2; ++a)
; #pragma unroll
;         for (int b = 0; b < 2; ++b)
; #pragma unroll
;             for (int m = 0; m < 4; ++m)
; #pragma unroll
;                 for (int n = 0; n < 2; ++n) acc[a][b][m][n] = (f32x4){0.f, 0.f, 0.f, 0.f};
;     h16x8 At[4][2], B0[2][2], B1[2][2];
;     const char* cA = P.a_tile(cur); const char* cB = P.b_tile(cur);
;     if constexpr (SP2) {
;         PG8_STAGE(PG8_SB(0, 0), cB, voffB); PG8_STAGE(PG8_SB(0, 1), cB + hstepB, voffB); PG8_STAGE(PG8_SA(0, 0), cA, voffA); PG8_STAGE(PG8_SA(0, 1), cA + hstepA, voffA);
;         if (wr == 1) PG8_BAR;
;         PG8_WAIT_V(2); PG8_BAR;
;         PG8_STAGE(PG8_SB(1, 0), cB + kstep, voffB); PG8_STAGE(PG8_SA(1, 0), cA + kstep, voffA); PG8_STAGE(PG8_SB(1, 1), cB + hstepB + kstep, voffB);
;         PG8_WAIT_V(6); PG8_BAR;
.LBB0_1059:
	v_readlane_b32 s6, v255, 1
	v_readlane_b32 s84, v251, 4
	s_mul_i32 s2, s6, 0x8400
	v_readlane_b32 s86, v251, 6
	v_readlane_b32 s87, v251, 7
	s_lshl_b64 s[4:5], s[2:3], 2
	s_mov_b64 s[46:47], s[86:87]
	s_add_u32 s22, s46, s4
	v_and_b32_e32 v1, 15, v0
	v_and_b32_e32 v2, 48, v0
	v_lshlrev_b32_e32 v0, 2, v0
	s_addc_u32 s23, s47, s5
	v_lshl_or_b32 v1, v1, 6, v2
	s_lshl_b32 s2, s64, 13
	v_and_b32_e32 v0, 32, v0
	s_lshl_b32 s1, s1, 5
	v_bitop3_b32 v2, v1, s2, v0 bitop3:0xde
	s_and_b32 s84, s1, 0x60
	s_mul_i32 s2, s6, 0x2c00
	s_lshl_b32 s1, s84, 7
	s_lshl_b64 s[4:5], s[2:3], 2
	v_bitop3_b32 v0, s1, v1, v0 bitop3:0xf6
	s_add_u32 s1, s30, s4
	s_addc_u32 s2, s31, s5
	s_add_u32 s28, s1, 0x200000
	s_addc_u32 s29, s2, 0
	v_readlane_b32 s85, v251, 5
	s_add_u32 s4, s44, 0x80
	s_waitcnt vmcnt(2)
	s_barrier
	s_addc_u32 s5, s45, 0
	s_add_i32 s2, s72, 0x18000
	s_mov_b32 s1, m0
	s_mov_b32 m0, s2
	s_nop 0
	global_load_lds_dwordx4 v217, s[4:5]
	s_mov_b32 m0, s1
	s_add_i32 s85, s72, 0x1a000
	s_mov_b32 s1, m0
	s_mov_b32 m0, s85
	s_nop 0
	global_load_lds_dwordx4 v248, s[4:5]
	s_mov_b32 m0, s1
	s_add_u32 s4, s60, 0x80
	s_addc_u32 s5, s61, 0
	s_add_i32 s86, s72, 0x8000
	s_mov_b32 s1, m0
	s_mov_b32 m0, s86
	s_nop 0
	global_load_lds_dwordx4 v250, s[4:5]
	s_mov_b32 m0, s1
	s_add_i32 s87, s72, 0xa000
	v_readlane_b32 s88, v251, 8
	s_mov_b32 s1, m0
	s_mov_b32 m0, s87
	s_nop 0
	global_load_lds_dwordx4 v247, s[4:5]
	s_mov_b32 m0, s1
	s_add_u32 s4, s44, 0x40080
	v_readlane_b32 s89, v251, 9
	s_addc_u32 s5, s45, 0
	s_add_i32 s88, s72, 0x1c000
	s_mov_b32 s1, m0
	s_mov_b32 m0, s88
	s_nop 0
	global_load_lds_dwordx4 v217, s[4:5]
	s_mov_b32 m0, s1
	v_readlane_b32 s90, v251, 10
	s_add_i32 s89, s72, 0x1e000
	s_mov_b32 s1, m0
	s_mov_b32 m0, s89
	s_nop 0
	global_load_lds_dwordx4 v248, s[4:5]
	s_mov_b32 m0, s1
	s_waitcnt vmcnt(6)
	s_add_i32 s90, s72, 0xc000
	v_readlane_b32 s91, v251, 11
	s_cmpk_lt_u32 s0, 0x100
	v_readlane_b32 s0, v252, 54
	s_cselect_b64 s[46:47], -1, 0
	s_lshl_b32 s91, s64, 7
	s_add_i32 s92, s72, 0xe000
	s_mov_b32 s93, 0
	v_add_u32_e32 v210, 0, v0
	v_add_u32_e32 v211, 0, v2
	v_readlane_b32 s94, v252, 35
	s_mov_b32 s95, s0
	s_barrier
	v_readlane_b32 s1, v252, 55
	s_branch .LBB0_1062
.LBB0_1062:
	s_add_i32 s93, s93, 1
	s_mul_i32 s0, s93, s71
	s_mul_hi_u32 s1, s93, s70
	s_add_i32 s1, s1, s0
	s_mul_i32 s0, s93, s70
	s_add_u32 s56, s0, s20
	s_addc_u32 s57, s1, s33
	s_cmp_lt_u32 s56, 0x2100
	s_cselect_b64 s[36:37], exec, 0
	s_cbranch_scc0 .LBB0_1064
	s_lshr_b32 s1, s56, 3
	s_and_b32 s0, s56, 7
	s_mul_i32 s0, s0, 0x420
	s_add_i32 s0, s0, s1
	s_mul_hi_i32 s1, s0, 0x2e8ba2e9
	s_lshr_b32 s4, s1, 31
	s_ashr_i32 s1, s1, 5
	s_add_i32 s1, s1, s4
	s_lshl_b32 s4, s1, 2
	s_sub_i32 s5, 0xc0, s4
	s_mulk_i32 s1, 0xb0
	s_sub_i32 s0, s0, s1
	s_lshr_b32 s48, s0, 2
	s_and_b32 s0, s0, 3
	s_add_i32 s50, s4, s0

;     __device__ __forceinline__ void operator()(Acc& acc, const Unit& u, int wr, int wc, int fr, int fq, LAS unsigned char* lds, int tid) const {
;     ...
;         if constexpr (I8) {
; #pragma unroll
;             for (int ai = 0; ai < 2; ++ai) { const f32x4 sa = ldf4(sx, tok0 + tl0 + 4u * ai);
; #pragma unroll
;                 for (int m = 0; m < 4; ++m)
; #pragma unroll
;                     for (int bj = 0; bj < 2; ++bj)
; #pragma unroll
;                         for (int n = 0; n < 2; ++n) { const pg8::i32x4 iv = __builtin_bit_cast(pg8::i32x4, acc[ai][bj][m][n]); acc[ai][bj][m][n] = __builtin_convertvector(iv, f32x4) * sa[m]; }
;                 asm volatile("" ::: "memory"); }
;         }
;         const unsigned bk = 2 * u.pm + wr;
;         const bool lvalid = (bk & 15) != 0, rvalid = (bk & 15) != 15;
; #pragma unroll
;         for (int bj = 0; bj < 2; ++bj) {
;             const unsigned colp = u.pn * 256 + bj * 128 + wc * 32 + 8 * fq;
;             const unsigned coll = bj * FF + u.pn * 128 + wc * 32 + 8 * fq;
; #pragma unroll
;             for (int n = 0; n < 2; ++n) {
;                 f32x4 c0 = ldf4(cw, coll + 4u * n), c1 = ldf4(cw, (unsigned)FF2 + coll + 4u * n), c2 = ldf4(cw, 2u * FF2 + coll + 4u * n);
;                 if constexpr (I8) { const f32x4 swv = ldf4(sw, colp + 4u * n); c0 = c0 * swv; c1 = c1 * swv; c2 = c2 * swv; }
;                 f32x4 hl = {0.f, 0.f, 0.f, 0.f}, hr = {0.f, 0.f, 0.f, 0.f};
;                 if (fr == 0 && lvalid) hl = ldf4(HALO, (2u * bk) * (unsigned)FF2 + colp + 4u * n);
;                 if (fr == 15 && rvalid) hr = ldf4(HALO, (2u * bk + 1u) * (unsigned)FF2 + colp + 4u * n);
; #pragma unroll
;                 for (int e = 0; e < 4; ++e) {
;                     const float prev = dpp_shr1(hl[e], acc[1][bj][3][n][e]);
;                     const float next = dpp_shl1(hr[e], acc[0][bj][0][n][e]);
;                     float left = prev;
; #pragma unroll
;                     for (int j = 0; j < 8; ++j) {
;                         const float cur = acc[j >> 2][bj][j & 3][n][e];
;                         const float nx = (j < 7) ? acc[(j + 1) >> 2][bj][(j + 1) & 3][n][e] : next;
;                         acc[j >> 2][bj][j & 3][n][e] = c0[e] * left + c1[e] * cur + c2[e] * nx;
;                         left = cur;
;                     }
;                 }
.LBB0_1084:
	s_or_b64 exec, exec, s[44:45]
	v_cvt_f32_i32_e32 v53, v53
	v_cvt_f32_i32_e32 v52, v52
	v_cvt_f32_i32_e32 v49, v49
	v_cvt_f32_i32_e32 v48, v48
	v_pk_mul_f32 v[136:137], v[136:137], v[132:133]
	v_pk_mul_f32 v[140:141], v[140:141], v[132:133]
	v_pk_mul_f32 v[120:121], v[136:137], v[120:121]
	v_pk_mul_f32 v[52:53], v[112:113], v[52:53] op_sel:[1,0]
	v_cvt_f32_i32_e32 v45, v45
	v_cvt_f32_i32_e32 v44, v44
	v_pk_mul_f32 v[138:139], v[138:139], v[134:135]
	v_pk_mul_f32 v[142:143], v[142:143], v[134:135]
	v_pk_mul_f32 v[134:135], v[130:131], v[134:135]
	v_pk_mul_f32 v[130:131], v[128:129], v[132:133]
	v_pk_fma_f32 v[120:121], v[224:225], v[140:141], v[120:121]
	v_cvt_f32_i32_e32 v41, v41
	v_cvt_f32_i32_e32 v40, v40
	v_pk_fma_f32 v[132:133], v[52:53], v[130:131], v[120:121]
	v_pk_mul_f32 v[120:121], v[52:53], v[140:141]
	v_pk_mul_f32 v[48:49], v[114:115], v[48:49] op_sel_hi:[0,1]
	v_cvt_f32_i32_e32 v37, v37
	v_cvt_f32_i32_e32 v36, v36
	v_pk_fma_f32 v[120:121], v[224:225], v[136:137], v[120:121]
	v_mov_b32_e32 v208, v115
	v_cvt_f32_i32_e32 v33, v33
	v_cvt_f32_i32_e32 v32, v32
	v_pk_fma_f32 v[128:129], v[48:49], v[130:131], v[120:121]
	v_pk_mul_f32 v[120:121], v[48:49], v[140:141]
	v_pk_mul_f32 v[44:45], v[208:209], v[44:45] op_sel_hi:[0,1]
	v_pk_fma_f32 v[52:53], v[52:53], v[136:137], v[120:121]
	v_pk_mul_f32 v[40:41], v[104:105], v[40:41] op_sel_hi:[0,1]
	v_pk_fma_f32 v[120:121], v[44:45], v[130:131], v[52:53]
	v_pk_mul_f32 v[52:53], v[44:45], v[140:141]
	v_cvt_f32_i32_e32 v55, v55
	v_cvt_f32_i32_e32 v54, v54
	v_pk_mul_f32 v[36:37], v[104:105], v[36:37] op_sel:[1,0]
	v_pk_fma_f32 v[48:49], v[48:49], v[136:137], v[52:53]
	v_pk_mul_f32 v[52:53], v[40:41], v[140:141]
	v_pk_mul_f32 v[32:33], v[106:107], v[32:33] op_sel_hi:[0,1]
	v_pk_fma_f32 v[44:45], v[44:45], v[136:137], v[52:53]
	v_pk_mul_f32 v[52:53], v[36:37], v[140:141]
	v_cvt_f32_i32_e32 v51, v51
	v_cvt_f32_i32_e32 v50, v50
	v_pk_fma_f32 v[48:49], v[40:41], v[130:131], v[48:49]
	v_pk_fma_f32 v[40:41], v[40:41], v[136:137], v[52:53]
	v_pk_mul_f32 v[52:53], v[32:33], v[140:141]
	v_pk_fma_f32 v[44:45], v[36:37], v[130:131], v[44:45]
	v_pk_fma_f32 v[36:37], v[36:37], v[136:137], v[52:53]
	v_pk_mul_f32 v[52:53], v[138:139], v[122:123]
	v_pk_mul_f32 v[54:55], v[112:113], v[54:55] op_sel:[1,0]
	v_cvt_f32_i32_e32 v47, v47
	v_cvt_f32_i32_e32 v46, v46
	v_pk_fma_f32 v[52:53], v[220:221], v[142:143], v[52:53]
	v_cvt_f32_i32_e32 v43, v43
	v_cvt_f32_i32_e32 v42, v42
	v_pk_fma_f32 v[40:41], v[32:33], v[130:131], v[40:41]
	v_pk_mul_f32 v[32:33], v[32:33], v[136:137]
	v_pk_fma_f32 v[136:137], v[54:55], v[134:135], v[52:53]
	v_pk_mul_f32 v[52:53], v[54:55], v[142:143]
	v_pk_mul_f32 v[50:51], v[114:115], v[50:51] op_sel_hi:[0,1]
	v_cvt_f32_i32_e32 v39, v39
	v_cvt_f32_i32_e32 v38, v38
	v_pk_fma_f32 v[32:33], v[222:223], v[140:141], v[32:33]
	v_pk_fma_f32 v[52:53], v[220:221], v[138:139], v[52:53]
	v_pk_fma_f32 v[36:37], v[222:223], v[130:131], v[36:37]
	v_pk_fma_f32 v[32:33], v[130:131], v[124:125], v[32:33]
	v_pk_fma_f32 v[130:131], v[50:51], v[134:135], v[52:53]
	v_pk_mul_f32 v[52:53], v[50:51], v[142:143]
	v_cvt_f32_i32_e32 v27, v27
	v_cvt_f32_i32_e32 v26, v26
	v_cvt_f32_i32_e32 v13, v13
	v_cvt_f32_i32_e32 v12, v12
	v_pk_mul_f32 v[46:47], v[208:209], v[46:47] op_sel_hi:[0,1]
	v_cvt_f32_i32_e32 v35, v35
	v_cvt_f32_i32_e32 v34, v34
	v_pk_fma_f32 v[52:53], v[54:55], v[138:139], v[52:53]
	v_cvt_f32_i32_e32 v101, v101
	v_cvt_f32_i32_e32 v100, v100
	v_cvt_f32_i32_e32 v97, v97
	v_cvt_f32_i32_e32 v96, v96
	v_pk_mul_f32 v[42:43], v[104:105], v[42:43] op_sel_hi:[0,1]
	v_pk_fma_f32 v[122:123], v[46:47], v[134:135], v[52:53]
	v_pk_mul_f32 v[52:53], v[46:47], v[142:143]
	v_cvt_f32_i32_e32 v93, v93
	v_cvt_f32_i32_e32 v92, v92
	v_pk_mul_f32 v[38:39], v[104:105], v[38:39] op_sel:[1,0]
	v_pk_fma_f32 v[50:51], v[50:51], v[138:139], v[52:53]
	v_pk_mul_f32 v[52:53], v[42:43], v[142:143]
	v_cvt_f32_i32_e32 v11, v11
	v_cvt_f32_i32_e32 v10, v10
	v_cvt_f32_i32_e32 v89, v89
	v_cvt_f32_i32_e32 v88, v88
	v_pk_mul_f32 v[214:215], v[190:191], v[202:203]
	v_pk_mul_f32 v[190:191], v[188:189], v[200:201]
	v_pk_fma_f32 v[46:47], v[46:47], v[138:139], v[52:53]
	v_pk_mul_f32 v[52:53], v[38:39], v[142:143]
	v_cvt_f32_i32_e32 v31, v31
	v_cvt_f32_i32_e32 v30, v30
	v_pk_mul_f32 v[124:125], v[112:113], v[26:27] op_sel:[1,0]
	v_cvt_f32_i32_e32 v17, v17
	v_cvt_f32_i32_e32 v16, v16
	v_pk_mul_f32 v[26:27], v[104:105], v[12:13] op_sel_hi:[0,1]
	v_cvt_f32_i32_e32 v13, v9
	v_cvt_f32_i32_e32 v12, v8
	v_cvt_f32_i32_e32 v85, v85
	v_cvt_f32_i32_e32 v84, v84
	v_pk_mul_f32 v[196:197], v[196:197], v[200:201]
	v_pk_mul_f32 v[176:177], v[190:191], v[176:177]
	v_pk_mul_f32 v[34:35], v[106:107], v[34:35] op_sel_hi:[0,1]
	v_pk_fma_f32 v[50:51], v[42:43], v[134:135], v[50:51]
	v_pk_fma_f32 v[42:43], v[42:43], v[138:139], v[52:53]
	v_pk_mul_f32 v[100:101], v[112:113], v[100:101] op_sel:[1,0]
	v_pk_mul_f32 v[96:97], v[114:115], v[96:97] op_sel_hi:[0,1]
	v_pk_mul_f32 v[192:193], v[192:193], v[200:201]
	v_pk_fma_f32 v[176:177], v[244:245], v[196:197], v[176:177]
	v_pk_fma_f32 v[42:43], v[34:35], v[134:135], v[42:43]
	v_pk_mul_f32 v[52:53], v[34:35], v[142:143]
	v_pk_mul_f32 v[34:35], v[34:35], v[138:139]
	v_pk_mul_f32 v[92:93], v[208:209], v[92:93] op_sel_hi:[0,1]
	v_cvt_f32_i32_e32 v77, v77
	v_cvt_f32_i32_e32 v79, v79
	v_cvt_f32_i32_e32 v78, v78
	v_cvt_f32_i32_e32 v76, v76
	v_pk_fma_f32 v[188:189], v[100:101], v[192:193], v[176:177]
	v_pk_mul_f32 v[176:177], v[100:101], v[196:197]
	v_pk_mul_f32 v[200:201], v[96:97], v[196:197]
	v_cvt_f32_i32_e32 v57, v57
	v_cvt_f32_i32_e32 v59, v59
	v_cvt_f32_i32_e32 v58, v58
	v_cvt_f32_i32_e32 v56, v56
;     __device__ __forceinline__ void operator()(Acc& acc, const Unit& u, int wr, int wc, int fr, int fq, LAS unsigned char* lds, int tid) const {
;     ...
;         if constexpr (I8) {
; #pragma unroll
;             for (int ai = 0; ai < 2; ++ai) { const f32x4 sa = ldf4(sx, tok0 + tl0 + 4u * ai);
; #pragma unroll
;                 for (int m = 0; m < 4; ++m)
; #pragma unroll
;                     for (int bj = 0; bj < 2; ++bj)
; #pragma unroll
;                         for (int n = 0; n < 2; ++n) { const pg8::i32x4 iv = __builtin_bit_cast(pg8::i32x4, acc[ai][bj][m][n]); acc[ai][bj][m][n] = __builtin_convertvector(iv, f32x4) * sa[m]; }
;                 asm volatile("" ::: "memory"); }
;         }
;         const unsigned bk = 2 * u.pm + wr;
;         const bool lvalid = (bk & 15) != 0, rvalid = (bk & 15) != 15;
; #pragma unroll
;         for (int bj = 0; bj < 2; ++bj) {
;             const unsigned colp = u.pn * 256 + bj * 128 + wc * 32 + 8 * fq;
;             const unsigned coll = bj * FF + u.pn * 128 + wc * 32 + 8 * fq;
; #pragma unroll
;             for (int n = 0; n < 2; ++n) {
;                 f32x4 c0 = ldf4(cw, coll + 4u * n), c1 = ldf4(cw, (unsigned)FF2 + coll + 4u * n), c2 = ldf4(cw, 2u * FF2 + coll + 4u * n);
;                 if constexpr (I8) { const f32x4 swv = ldf4(sw, colp + 4u * n); c0 = c0 * swv; c1 = c1 * swv; c2 = c2 * swv; }
;                 f32x4 hl = {0.f, 0.f, 0.f, 0.f}, hr = {0.f, 0.f, 0.f, 0.f};
;                 if (fr == 0 && lvalid) hl = ldf4(HALO, (2u * bk) * (unsigned)FF2 + colp + 4u * n);
;                 if (fr == 15 && rvalid) hr = ldf4(HALO, (2u * bk + 1u) * (unsigned)FF2 + colp + 4u * n);
; #pragma unroll
;                 for (int e = 0; e < 4; ++e) {
;                     const float prev = dpp_shr1(hl[e], acc[1][bj][3][n][e]);
;                     const float next = dpp_shl1(hr[e], acc[0][bj][0][n][e]);
;                     float left = prev;
; #pragma unroll
;                     for (int j = 0; j < 8; ++j) {
;                         const float cur = acc[j >> 2][bj][j & 3][n][e];
;                         const float nx = (j < 7) ? acc[(j + 1) >> 2][bj][(j + 1) & 3][n][e] : next;
;                         acc[j >> 2][bj][j & 3][n][e] = c0[e] * left + c1[e] * cur + c2[e] * nx;
;                         left = cur;
;                     }
;                 }
;                 asm volatile("" ::: "memory");
;             }
	v_pk_fma_f32 v[46:47], v[38:39], v[134:135], v[46:47]
	v_pk_fma_f32 v[38:39], v[38:39], v[138:139], v[52:53]
	v_pk_fma_f32 v[34:35], v[218:219], v[142:143], v[34:35]
	v_mov_b32_e32 v52, v112
	v_mov_b32_e32 v53, v112
	v_pk_mul_f32 v[8:9], v[104:105], v[10:11] op_sel:[1,0]
	v_cvt_f32_i32_e32 v7, v7
	v_cvt_f32_i32_e32 v6, v6
	v_cvt_f32_i32_e32 v11, v5
	v_cvt_f32_i32_e32 v10, v4
	v_pk_mul_f32 v[88:89], v[104:105], v[88:89] op_sel_hi:[0,1]
	v_pk_fma_f32 v[176:177], v[244:245], v[190:191], v[176:177]
	v_pk_fma_f32 v[100:101], v[100:101], v[190:191], v[200:201]
	v_pk_mul_f32 v[200:201], v[92:93], v[196:197]
	v_pk_fma_f32 v[34:35], v[134:135], v[126:127], v[34:35]
	v_pk_mul_f32 v[126:127], v[52:53], v[30:31]
	v_pk_mul_f32 v[30:31], v[208:209], v[16:17] op_sel_hi:[0,1]
	v_pk_mul_f32 v[16:17], v[104:105], v[12:13] op_sel:[1,0]
	v_cvt_f32_i32_e32 v13, v3
	v_cvt_f32_i32_e32 v12, v2
	v_cvt_f32_i32_e32 v103, v103
	v_cvt_f32_i32_e32 v102, v102
	v_cvt_f32_i32_e32 v99, v99
	v_cvt_f32_i32_e32 v98, v98
	v_pk_mul_f32 v[84:85], v[104:105], v[84:85] op_sel:[1,0]
	v_pk_fma_f32 v[176:177], v[96:97], v[192:193], v[176:177]
	v_pk_fma_f32 v[96:97], v[96:97], v[190:191], v[200:201]
	v_pk_mul_f32 v[200:201], v[88:89], v[196:197]
	v_cvt_f32_i32_e32 v95, v95
	v_cvt_f32_i32_e32 v94, v94
	v_pk_fma_f32 v[100:101], v[92:93], v[192:193], v[100:101]
	v_pk_fma_f32 v[92:93], v[92:93], v[190:191], v[200:201]
	v_pk_mul_f32 v[200:201], v[84:85], v[196:197]
	v_cvt_f32_i32_e32 v91, v91
	v_cvt_f32_i32_e32 v90, v90
	v_pk_mul_f32 v[78:79], v[106:107], v[78:79] op_sel_hi:[0,1]
	v_pk_mul_f32 v[76:77], v[106:107], v[76:77] op_sel_hi:[0,1]
	v_pk_fma_f32 v[96:97], v[88:89], v[192:193], v[96:97]
	v_pk_fma_f32 v[88:89], v[88:89], v[190:191], v[200:201]
	v_pk_mul_f32 v[58:59], v[106:107], v[58:59] op_sel_hi:[0,1]
	v_pk_mul_f32 v[56:57], v[106:107], v[56:57] op_sel_hi:[0,1]
	v_pk_mul_f32 v[4:5], v[106:107], v[6:7] op_sel_hi:[0,1]
	v_pk_mul_f32 v[2:3], v[106:107], v[10:11] op_sel_hi:[0,1]
	v_mov_b32_e32 v106, v107
	v_pk_mul_f32 v[10:11], v[132:133], s[100:101] op_sel_hi:[1,0]
	v_cvt_f32_i32_e32 v87, v87
	v_cvt_f32_i32_e32 v86, v86
	v_pk_mul_f32 v[198:199], v[198:199], v[202:203]
	v_pk_fma_f32 v[88:89], v[76:77], v[192:193], v[88:89]
	v_pk_mul_f32 v[200:201], v[76:77], v[196:197]
	v_pk_mul_f32 v[76:77], v[76:77], v[190:191]
	v_pk_mul_f32 v[178:179], v[214:215], v[178:179]
	v_cvt_f32_i32_e32 v7, v1
	v_cvt_f32_i32_e32 v6, v0
	v_pk_mul_f32 v[0:1], v[106:107], v[12:13]
	v_exp_f32_e32 v10, v10
	v_exp_f32_e32 v11, v11
	v_pk_mul_f32 v[12:13], v[136:137], s[100:101] op_sel_hi:[1,0]
	v_pk_mul_f32 v[102:103], v[112:113], v[102:103] op_sel:[1,0]
	v_pk_mul_f32 v[98:99], v[114:115], v[98:99] op_sel_hi:[0,1]
	v_pk_mul_f32 v[194:195], v[194:195], v[202:203]
	v_pk_fma_f32 v[92:93], v[84:85], v[192:193], v[92:93]
	v_pk_fma_f32 v[84:85], v[84:85], v[190:191], v[200:201]
	v_pk_fma_f32 v[76:77], v[242:243], v[196:197], v[76:77]
	v_pk_fma_f32 v[178:179], v[240:241], v[198:199], v[178:179]
	v_exp_f32_e32 v12, v12
	v_exp_f32_e32 v13, v13
	v_pk_mul_f32 v[94:95], v[208:209], v[94:95] op_sel_hi:[0,1]
	v_pk_fma_f32 v[84:85], v[242:243], v[192:193], v[84:85]
	v_pk_fma_f32 v[76:77], v[192:193], v[204:205], v[76:77]
	v_pk_fma_f32 v[190:191], v[102:103], v[194:195], v[178:179]
	v_pk_mul_f32 v[178:179], v[102:103], v[198:199]
	v_pk_mul_f32 v[192:193], v[98:99], v[198:199]
	v_pk_mul_f32 v[90:91], v[104:105], v[90:91] op_sel_hi:[0,1]
	v_pk_fma_f32 v[178:179], v[240:241], v[214:215], v[178:179]
	v_pk_fma_f32 v[102:103], v[102:103], v[214:215], v[192:193]
	v_pk_mul_f32 v[192:193], v[94:95], v[198:199]
	v_pk_mul_f32 v[86:87], v[104:105], v[86:87] op_sel:[1,0]
	v_pk_fma_f32 v[178:179], v[98:99], v[194:195], v[178:179]
	v_pk_fma_f32 v[98:99], v[98:99], v[214:215], v[192:193]
	v_pk_mul_f32 v[192:193], v[90:91], v[198:199]
	v_cvt_f32_i32_e32 v81, v81
	v_cvt_f32_i32_e32 v80, v80
	v_cvt_f32_i32_e32 v73, v73
	v_cvt_f32_i32_e32 v72, v72
	v_pk_add_f32 v[10:11], v[10:11], 1.0 op_sel_hi:[1,0]
	v_pk_fma_f32 v[102:103], v[94:95], v[194:195], v[102:103]
	v_pk_fma_f32 v[94:95], v[94:95], v[214:215], v[192:193]
	v_pk_mul_f32 v[192:193], v[86:87], v[198:199]
	v_cvt_f32_i32_e32 v69, v69
	v_cvt_f32_i32_e32 v68, v68
	v_rcp_f32_e32 v10, v10
	v_rcp_f32_e32 v11, v11
	v_pk_add_f32 v[12:13], v[12:13], 1.0 op_sel_hi:[1,0]
	v_pk_fma_f32 v[98:99], v[90:91], v[194:195], v[98:99]
	v_pk_fma_f32 v[90:91], v[90:91], v[214:215], v[192:193]
	v_pk_mul_f32 v[192:193], v[78:79], v[198:199]
	v_cvt_f32_i32_e32 v65, v65
	v_cvt_f32_i32_e32 v64, v64
	v_pk_mul_f32 v[160:161], v[160:161], v[168:169]
	v_rcp_f32_e32 v12, v12
	v_rcp_f32_e32 v13, v13
	v_pk_fma_f32 v[94:95], v[86:87], v[194:195], v[94:95]
	v_pk_fma_f32 v[86:87], v[86:87], v[214:215], v[192:193]
	v_cvt_f32_i32_e32 v61, v61
	v_cvt_f32_i32_e32 v60, v60
	v_pk_mul_f32 v[192:193], v[158:159], v[170:171]
	v_pk_mul_f32 v[158:159], v[156:157], v[168:169]
	v_pk_mul_f32 v[144:145], v[160:161], v[144:145]
	v_pk_mul_f32 v[80:81], v[112:113], v[80:81] op_sel:[1,0]
	v_pk_mul_f32 v[72:73], v[114:115], v[72:73] op_sel_hi:[0,1]
	v_pk_mul_f32 v[164:165], v[164:165], v[168:169]
	v_pk_fma_f32 v[144:145], v[236:237], v[158:159], v[144:145]
	v_pk_mul_f32 v[68:69], v[208:209], v[68:69] op_sel_hi:[0,1]
	v_pk_fma_f32 v[156:157], v[80:81], v[164:165], v[144:145]
;     __device__ bool next(int i, Unit& u) const {
;     __device__ __forceinline__ void operator()(Acc& acc, const Unit& u, int wr, int wc, int fr, int fq, LAS unsigned char* lds, int tid) const {
;     ...
;         for (int bj = 0; bj < 2; ++bj) {
;             const unsigned colp = u.pn * 256 + bj * 128 + wc * 32 + 8 * fq;
;             const unsigned coll = bj * FF + u.pn * 128 + wc * 32 + 8 * fq;
; #pragma unroll
;             for (int n = 0; n < 2; ++n) {
;                 f32x4 c0 = ldf4(cw, coll + 4u * n), c1 = ldf4(cw, (unsigned)FF2 + coll + 4u * n), c2 = ldf4(cw, 2u * FF2 + coll + 4u * n);
;                 if constexpr (I8) { const f32x4 swv = ldf4(sw, colp + 4u * n); c0 = c0 * swv; c1 = c1 * swv; c2 = c2 * swv; }
;                 f32x4 hl = {0.f, 0.f, 0.f, 0.f}, hr = {0.f, 0.f, 0.f, 0.f};
;                 if (fr == 0 && lvalid) hl = ldf4(HALO, (2u * bk) * (unsigned)FF2 + colp + 4u * n);
;                 if (fr == 15 && rvalid) hr = ldf4(HALO, (2u * bk + 1u) * (unsigned)FF2 + colp + 4u * n);
; #pragma unroll
;                 for (int e = 0; e < 4; ++e) {
;                     const float prev = dpp_shr1(hl[e], acc[1][bj][3][n][e]);
;                     const float next = dpp_shl1(hr[e], acc[0][bj][0][n][e]);
;                     float left = prev;
; #pragma unroll
;                     for (int j = 0; j < 8; ++j) {
;                         const float cur = acc[j >> 2][bj][j & 3][n][e];
;                         const float nx = (j < 7) ? acc[(j + 1) >> 2][bj][(j + 1) & 3][n][e] : next;
;                         acc[j >> 2][bj][j & 3][n][e] = c0[e] * left + c1[e] * cur + c2[e] * nx;
;                         left = cur;
;                     }
;                 }
;                 asm volatile("" ::: "memory");
;             }
;         }
;         const unsigned colo = u.pn * 128 + wc * 32 + 8 * fq;
; #pragma unroll
;         for (int ai = 0; ai < 2; ++ai)
; #pragma unroll
;             for (int m = 0; m < 4; ++m) {
;                 f32x4 a[2];
; #pragma unroll
;                 for (int n = 0; n < 2; ++n)
; #pragma unroll
;                     for (int e = 0; e < 4; ++e) a[n][e] = silu_f(acc[ai][0][m][n][e]) * acc[ai][1][m][n][e];
;                 store_h8_nt((h16*)((char*)ACT + (((tok0 + tl0 + 4u * ai + m) * (unsigned)FF + colo) << 1)), a[0], a[1]);
;                 asm volatile("" ::: "memory");
;             }
	v_pk_mul_f32 v[144:145], v[80:81], v[158:159]
	v_pk_mul_f32 v[168:169], v[72:73], v[158:159]
	v_pk_mul_f32 v[10:11], v[132:133], v[10:11]
	v_cvt_f32_i32_e32 v83, v83
	v_cvt_f32_i32_e32 v82, v82
	v_pk_mul_f32 v[64:65], v[104:105], v[64:65] op_sel_hi:[0,1]
	v_pk_fma_f32 v[144:145], v[236:237], v[160:161], v[144:145]
	v_pk_fma_f32 v[80:81], v[80:81], v[160:161], v[168:169]
	v_pk_mul_f32 v[168:169], v[68:69], v[158:159]
	v_pk_mul_f32 v[106:107], v[10:11], v[188:189]
	v_pk_mul_f32 v[10:11], v[136:137], v[12:13]
	v_mul_f32_e32 v12, 0xbfb8aa3b, v156
	v_pk_mul_f32 v[60:61], v[104:105], v[60:61] op_sel:[1,0]
	v_pk_fma_f32 v[144:145], v[72:73], v[164:165], v[144:145]
	v_pk_fma_f32 v[72:73], v[72:73], v[160:161], v[168:169]
	v_pk_mul_f32 v[168:169], v[64:65], v[158:159]
	v_exp_f32_e32 v12, v12
	v_mul_f32_e32 v13, 0xbfb8aa3b, v157
	v_cvt_f32_i32_e32 v67, v67
	v_cvt_f32_i32_e32 v66, v66
	v_cvt_f32_i32_e32 v63, v63
	v_cvt_f32_i32_e32 v62, v62
	v_pk_mul_f32 v[162:163], v[162:163], v[170:171]
	v_pk_fma_f32 v[80:81], v[68:69], v[164:165], v[80:81]
	v_pk_fma_f32 v[68:69], v[68:69], v[160:161], v[168:169]
	v_pk_mul_f32 v[168:169], v[60:61], v[158:159]
	v_cvt_f32_i32_e32 v29, v29
	v_cvt_f32_i32_e32 v28, v28
	v_cvt_f32_i32_e32 v25, v25
	v_cvt_f32_i32_e32 v24, v24
	v_cvt_f32_i32_e32 v19, v19
	v_cvt_f32_i32_e32 v18, v18
	v_cvt_f32_i32_e32 v15, v15
	v_cvt_f32_i32_e32 v14, v14
	v_exp_f32_e32 v13, v13
	v_pk_fma_f32 v[72:73], v[64:65], v[164:165], v[72:73]
	v_pk_fma_f32 v[64:65], v[64:65], v[160:161], v[168:169]
	v_pk_mul_f32 v[146:147], v[162:163], v[146:147]
	v_pk_mul_f32 v[82:83], v[112:113], v[82:83] op_sel:[1,0]
	v_pk_mul_f32 v[166:167], v[166:167], v[170:171]
	v_pk_fma_f32 v[64:65], v[56:57], v[164:165], v[64:65]
	v_pk_mul_f32 v[168:169], v[56:57], v[158:159]
	v_pk_mul_f32 v[56:57], v[56:57], v[160:161]
	v_pk_fma_f32 v[146:147], v[232:233], v[192:193], v[146:147]
	v_cvt_f32_i32_e32 v75, v75
	v_cvt_f32_i32_e32 v74, v74
	v_pk_fma_f32 v[56:57], v[234:235], v[158:159], v[56:57]
	v_pk_fma_f32 v[158:159], v[82:83], v[166:167], v[146:147]
	v_cvt_f32_i32_e32 v23, v23
	v_cvt_f32_i32_e32 v22, v22
	v_cvt_f32_i32_e32 v21, v21
	v_cvt_f32_i32_e32 v20, v20
	v_pk_mul_f32 v[132:133], v[10:11], v[190:191]
	v_add_f32_e32 v10, 1.0, v12
	v_pk_mul_f32 v[66:67], v[104:105], v[66:67] op_sel_hi:[0,1]
	v_pk_mul_f32 v[62:63], v[104:105], v[62:63] op_sel:[1,0]
	v_pk_fma_f32 v[38:39], v[218:219], v[134:135], v[38:39]
	v_pk_mul_f32 v[134:135], v[228:229], v[28:29]
	v_pk_mul_f32 v[112:113], v[112:113], v[24:25] op_sel:[1,0]
	v_pk_mul_f32 v[28:29], v[208:209], v[18:19] op_sel_hi:[0,1]
	v_pk_mul_f32 v[24:25], v[104:105], v[14:15] op_sel_hi:[0,1]
	v_rcp_f32_e32 v104, v10
	v_add_f32_e32 v10, 1.0, v13
	s_waitcnt vmcnt(0)
	v_pk_mul_f32 v[18:19], v[116:117], v[180:181]
	v_mul_f32_e32 v116, 0xbfb8aa3b, v158
	v_pk_mul_f32 v[6:7], v[226:227], v[6:7]
	v_rcp_f32_e32 v105, v10
	v_pk_mul_f32 v[10:11], v[118:119], v[182:183]
	v_exp_f32_e32 v118, v116
	v_mul_f32_e32 v116, 0xbfb8aa3b, v159
	v_mov_b32_dpp v148, v6 row_shr:1 row_mask:0xf bank_mask:0xf
	v_mov_b32_dpp v149, v7 row_shr:1 row_mask:0xf bank_mask:0xf
	v_exp_f32_e32 v119, v116
	v_pk_mul_f32 v[74:75], v[114:115], v[74:75] op_sel_hi:[0,1]
	v_pk_mul_f32 v[52:53], v[114:115], v[22:23] op_sel_hi:[0,1]
	v_pk_mul_f32 v[54:55], v[114:115], v[20:21] op_sel_hi:[0,1]
	v_pk_mul_f32 v[20:21], v[184:185], v[180:181]
	v_pk_mul_f32 v[114:115], v[18:19], v[148:149]
	v_pk_mul_f32 v[22:23], v[152:153], v[180:181]
	v_pk_fma_f32 v[114:115], v[134:135], v[20:21], v[114:115]
	v_pk_mul_f32 v[104:105], v[156:157], v[104:105]
	v_pk_fma_f32 v[114:115], v[112:113], v[22:23], v[114:115]
	v_mov_b32_dpp v150, v0 row_shr:1 row_mask:0xf bank_mask:0xf
	v_pk_mul_f32 v[116:117], v[104:105], v[114:115]
	v_pk_add_f32 v[104:105], v[118:119], 1.0 op_sel_hi:[1,0]
	v_rcp_f32_e32 v104, v104
	v_rcp_f32_e32 v105, v105
	v_mov_b32_dpp v151, v1 row_shr:1 row_mask:0xf bank_mask:0xf
	v_pk_mul_f32 v[12:13], v[186:187], v[182:183]
	v_pk_mul_f32 v[114:115], v[10:11], v[150:151]
	v_pk_mul_f32 v[14:15], v[154:155], v[182:183]
	v_pk_fma_f32 v[114:115], v[126:127], v[12:13], v[114:115]
	v_pk_mul_f32 v[104:105], v[158:159], v[104:105]
	v_pk_fma_f32 v[114:115], v[124:125], v[14:15], v[114:115]
	s_movk_i32 s0, 0x1600
	v_pk_mul_f32 v[118:119], v[104:105], v[114:115]
	v_mul_f32_e32 v105, 0xbfb8aa3b, v128
	v_cvt_pk_f16_f32 v114, v106, v107
	v_exp_f32_e32 v105, v105
	v_mul_f32_e32 v106, 0xbfb8aa3b, v129
	v_exp_f32_e32 v107, v106
	v_mul_lo_u32 v104, v212, s0
	s_mov_b32 s101, s36
	s_mov_b32 s94, s48
	s_mov_b32 s95, s50
	s_mov_b64 s[44:45], s[76:77]
	s_mov_b64 s[60:61], s[56:57]
	s_cmp_eq_u32 s101, 0
	s_cbranch_scc1 .Lh1065_skip
	s_add_i32 s93, s93, 1
	s_mul_i32 s0, s93, s71
	s_mul_hi_u32 s1, s93, s70
	s_add_i32 s1, s1, s0
	s_mul_i32 s0, s93, s70
	s_add_u32 s56, s0, s20
	s_addc_u32 s57, s1, s33
	s_cmp_lt_u32 s56, 0x2100
	s_cselect_b64 s[36:37], exec, 0
	s_cbranch_scc0 .Lh1065_pre
	s_lshr_b32 s1, s56, 3
	s_and_b32 s0, s56, 7
	s_mul_i32 s0, s0, 0x420
	s_add_i32 s0, s0, s1
	s_mul_hi_i32 s1, s0, 0x2e8ba2e9
	s_lshr_b32 s4, s1, 31
	s_ashr_i32 s1, s1, 5
	s_add_i32 s1, s1, s4
	s_lshl_b32 s4, s1, 2
	s_sub_i32 s5, 0xc0, s4
	s_mulk_i32 s1, 0xb0
	s_sub_i32 s0, s0, s1
	s_lshr_b32 s48, s0, 2
	s_and_b32 s0, s0, 3
	s_add_i32 s50, s4, s0

;     __device__ __forceinline__ void operator()(Acc& acc, const Unit& u, int wr, int wc, int fr, int fq, LAS unsigned char* lds, int tid) const {
;     ...
; #pragma unroll
;         for (int bj = 0; bj < 2; ++bj) {
;             const unsigned colp = u.pn * 256 + bj * 128 + wc * 32 + 8 * fq;
;             const unsigned coll = bj * FF + u.pn * 128 + wc * 32 + 8 * fq;
; #pragma unroll
;             for (int n = 0; n < 2; ++n) {
;                 f32x4 c0 = ldf4(cw, coll + 4u * n), c1 = ldf4(cw, (unsigned)FF2 + coll + 4u * n), c2 = ldf4(cw, 2u * FF2 + coll + 4u * n);
;                 if constexpr (I8) { const f32x4 swv = ldf4(sw, colp + 4u * n); c0 = c0 * swv; c1 = c1 * swv; c2 = c2 * swv; }
;                 f32x4 hl = {0.f, 0.f, 0.f, 0.f}, hr = {0.f, 0.f, 0.f, 0.f};
;                 if (fr == 0 && lvalid) hl = ldf4(HALO, (2u * bk) * (unsigned)FF2 + colp + 4u * n);
;                 if (fr == 15 && rvalid) hr = ldf4(HALO, (2u * bk + 1u) * (unsigned)FF2 + colp + 4u * n);
; #pragma unroll
;                 for (int e = 0; e < 4; ++e) {
;                     const float prev = dpp_shr1(hl[e], acc[1][bj][3][n][e]);
;                     const float next = dpp_shl1(hr[e], acc[0][bj][0][n][e]);
;                     float left = prev;
; #pragma unroll
;                     for (int j = 0; j < 8; ++j) {
;                         const float cur = acc[j >> 2][bj][j & 3][n][e];
;                         const float nx = (j < 7) ? acc[(j + 1) >> 2][bj][(j + 1) & 3][n][e] : next;
;                         acc[j >> 2][bj][j & 3][n][e] = c0[e] * left + c1[e] * cur + c2[e] * nx;
;                         left = cur;
;                     }
;                 }
;                 asm volatile("" ::: "memory");
;             }
;         }
;         const unsigned colo = u.pn * 128 + wc * 32 + 8 * fq;
; #pragma unroll
;         for (int ai = 0; ai < 2; ++ai)
; #pragma unroll
;             for (int m = 0; m < 4; ++m) {
;                 f32x4 a[2];
; #pragma unroll
;                 for (int n = 0; n < 2; ++n)
; #pragma unroll
;                     for (int e = 0; e < 4; ++e) a[n][e] = silu_f(acc[ai][0][m][n][e]) * acc[ai][1][m][n][e];
;                 store_h8_nt((h16*)((char*)ACT + (((tok0 + tl0 + 4u * ai + m) * (unsigned)FF + colo) << 1)), a[0], a[1]);
;                 asm volatile("" ::: "memory");
;             }
.Lh1065_skip:
	v_add_f32_e32 v105, 1.0, v105
	v_add_lshl_u32 v104, v104, v213, 1
	v_cvt_pk_f16_f32 v115, v132, v133
	v_cvt_pk_f16_f32 v116, v116, v117
	v_cvt_pk_f16_f32 v117, v118, v119
	v_rcp_f32_e32 v106, v105
	v_add_f32_e32 v105, 1.0, v107
	v_mul_f32_e32 v107, 0xbfb8aa3b, v130
	global_store_dwordx4 v104, v[114:117], s[14:15] nt
	v_pk_mul_f32 v[146:147], v[82:83], v[192:193]
	v_mov_b32_dpp v110, v126 row_shl:1 row_mask:0xf bank_mask:0xf
	v_exp_f32_e32 v114, v107
	v_mul_f32_e32 v107, 0xbfb8aa3b, v131
	v_exp_f32_e32 v115, v107
	v_rcp_f32_e32 v107, v105
	v_add_f32_e32 v105, 1.0, v114
	v_rcp_f32_e32 v114, v105
	v_add_f32_e32 v105, 1.0, v115
	v_rcp_f32_e32 v115, v105
	v_mul_f32_e32 v105, 0xbfb8aa3b, v144
	v_exp_f32_e32 v105, v105
	v_mul_f32_e32 v116, 0xbfb8aa3b, v145
	v_exp_f32_e32 v118, v116
	v_pk_fma_f32 v[146:147], v[232:233], v[162:163], v[146:147]
	v_pk_mul_f32 v[114:115], v[130:131], v[114:115]
	v_add_f32_e32 v105, 1.0, v105
	v_pk_fma_f32 v[146:147], v[74:75], v[166:167], v[146:147]
	v_pk_mul_f32 v[116:117], v[114:115], v[178:179]
	v_rcp_f32_e32 v114, v105
	v_add_f32_e32 v105, 1.0, v118
	v_rcp_f32_e32 v115, v105
	v_mul_f32_e32 v105, 0xbfb8aa3b, v146
	v_pk_mul_f32 v[106:107], v[128:129], v[106:107]
	v_exp_f32_e32 v105, v105
	v_mul_f32_e32 v128, 0xbfb8aa3b, v147
	v_exp_f32_e32 v128, v128
	v_pk_mul_f32 v[118:119], v[112:113], v[20:21]
	v_pk_mul_f32 v[114:115], v[144:145], v[114:115]
	v_pk_fma_f32 v[118:119], v[134:135], v[18:19], v[118:119]
	v_add_f32_e32 v105, 1.0, v105
	v_pk_fma_f32 v[118:119], v[54:55], v[22:23], v[118:119]
	v_mov_b32_dpp v111, v127 row_shl:1 row_mask:0xf bank_mask:0xf
	v_pk_mul_f32 v[118:119], v[114:115], v[118:119]
	v_rcp_f32_e32 v114, v105
	v_add_f32_e32 v105, 1.0, v128
	v_rcp_f32_e32 v115, v105
	v_pk_mul_f32 v[128:129], v[124:125], v[12:13]
	v_pk_mul_f32 v[106:107], v[106:107], v[176:177]
	v_pk_fma_f32 v[126:127], v[126:127], v[10:11], v[128:129]
	v_pk_mul_f32 v[114:115], v[146:147], v[114:115]
	v_pk_fma_f32 v[126:127], v[52:53], v[14:15], v[126:127]
	v_add_u32_e32 v105, 0x2c00, v104
	v_pk_mul_f32 v[126:127], v[114:115], v[126:127]
	v_cvt_pk_f16_f32 v114, v106, v107
	v_mul_f32_e32 v106, 0xbfb8aa3b, v120
	v_exp_f32_e32 v106, v106
	v_mul_f32_e32 v107, 0xbfb8aa3b, v121
	v_exp_f32_e32 v107, v107
	v_cvt_pk_f16_f32 v115, v116, v117
	v_cvt_pk_f16_f32 v116, v118, v119
	v_cvt_pk_f16_f32 v117, v126, v127
	global_store_dwordx4 v105, v[114:117], s[14:15] nt
	v_add_f32_e32 v105, 1.0, v106
	v_rcp_f32_e32 v106, v105
	v_add_f32_e32 v105, 1.0, v107
	v_mul_f32_e32 v107, 0xbfb8aa3b, v122
	v_exp_f32_e32 v114, v107
	v_mul_f32_e32 v107, 0xbfb8aa3b, v123
	v_exp_f32_e32 v115, v107
	v_rcp_f32_e32 v107, v105
	v_add_f32_e32 v105, 1.0, v114
	v_rcp_f32_e32 v114, v105
	v_add_f32_e32 v105, 1.0, v115
	v_rcp_f32_e32 v115, v105
	v_pk_mul_f32 v[106:107], v[120:121], v[106:107]
	v_mul_f32_e32 v105, 0xbfb8aa3b, v80
	v_pk_mul_f32 v[100:101], v[106:107], v[100:101]
	v_pk_mul_f32 v[106:107], v[122:123], v[114:115]
	v_exp_f32_e32 v105, v105
	v_mul_f32_e32 v114, 0xbfb8aa3b, v81
	v_exp_f32_e32 v114, v114
	v_cvt_f32_i32_e32 v71, v71
	v_cvt_f32_i32_e32 v70, v70
	v_add_f32_e32 v105, 1.0, v105
	v_pk_mul_f32 v[102:103], v[106:107], v[102:103]
	v_rcp_f32_e32 v106, v105
	v_add_f32_e32 v105, 1.0, v114
	v_rcp_f32_e32 v107, v105
	v_pk_fma_f32 v[68:69], v[60:61], v[164:165], v[68:69]
	v_pk_fma_f32 v[60:61], v[60:61], v[160:161], v[168:169]
	v_pk_mul_f32 v[160:161], v[74:75], v[192:193]
	v_pk_mul_f32 v[70:71], v[208:209], v[70:71] op_sel_hi:[0,1]
	v_pk_fma_f32 v[82:83], v[82:83], v[162:163], v[160:161]
	v_pk_mul_f32 v[114:115], v[54:55], v[20:21]
	v_pk_fma_f32 v[82:83], v[70:71], v[166:167], v[82:83]
	v_pk_mul_f32 v[80:81], v[80:81], v[106:107]
	v_mul_f32_e32 v105, 0xbfb8aa3b, v82
	v_mul_f32_e32 v106, 0xbfb8aa3b, v83
	v_pk_fma_f32 v[112:113], v[112:113], v[18:19], v[114:115]
	v_exp_f32_e32 v105, v105
	v_exp_f32_e32 v114, v106
	v_pk_fma_f32 v[112:113], v[30:31], v[22:23], v[112:113]
	v_pk_mul_f32 v[160:161], v[70:71], v[192:193]
	v_pk_mul_f32 v[106:107], v[80:81], v[112:113]
	v_add_f32_e32 v80, 1.0, v105
	v_add_f32_e32 v81, 1.0, v114
	v_rcp_f32_e32 v80, v80
	v_rcp_f32_e32 v81, v81
	v_pk_mul_f32 v[112:113], v[52:53], v[12:13]
	v_add_u32_e32 v105, 0x5800, v104
	v_pk_fma_f32 v[112:113], v[124:125], v[10:11], v[112:113]
	v_pk_mul_f32 v[80:81], v[82:83], v[80:81]
	v_pk_fma_f32 v[112:113], v[28:29], v[14:15], v[112:113]
	v_cvt_pk_f16_f32 v82, v106, v107
	v_pk_mul_f32 v[112:113], v[80:81], v[112:113]
	v_cvt_pk_f16_f32 v80, v100, v101
	v_pk_mul_f32 v[100:101], v[48:49], s[100:101] op_sel_hi:[1,0]
	v_exp_f32_e32 v100, v100
	v_exp_f32_e32 v101, v101
	v_cvt_pk_f16_f32 v81, v102, v103
	v_cvt_pk_f16_f32 v83, v112, v113
	global_store_dwordx4 v105, v[80:83], s[14:15] nt
	v_pk_fma_f32 v[74:75], v[74:75], v[162:163], v[160:161]
	v_pk_mul_f32 v[160:161], v[66:67], v[192:193]
	v_pk_add_f32 v[80:81], v[100:101], 1.0 op_sel_hi:[1,0]
	v_rcp_f32_e32 v80, v80
	v_rcp_f32_e32 v81, v81
	v_pk_mul_f32 v[82:83], v[50:51], s[100:101] op_sel_hi:[1,0]
	v_exp_f32_e32 v82, v82
	v_pk_mul_f32 v[48:49], v[48:49], v[80:81]
	v_pk_mul_f32 v[80:81], v[72:73], s[100:101] op_sel_hi:[1,0]
	v_exp_f32_e32 v80, v80
	v_exp_f32_e32 v81, v81
	v_exp_f32_e32 v83, v83
	v_pk_add_f32 v[80:81], v[80:81], 1.0 op_sel_hi:[1,0]
	v_rcp_f32_e32 v80, v80
	v_rcp_f32_e32 v81, v81
	v_pk_add_f32 v[82:83], v[82:83], 1.0 op_sel_hi:[1,0]
	v_rcp_f32_e32 v82, v82
	v_rcp_f32_e32 v83, v83
	v_pk_fma_f32 v[74:75], v[66:67], v[166:167], v[74:75]
	v_pk_mul_f32 v[72:73], v[72:73], v[80:81]
	v_pk_mul_f32 v[80:81], v[74:75], s[100:101] op_sel_hi:[1,0]
	v_exp_f32_e32 v80, v80
	v_exp_f32_e32 v81, v81
	v_pk_mul_f32 v[50:51], v[50:51], v[82:83]
;     __device__ __forceinline__ void operator()(Acc& acc, const Unit& u, int wr, int wc, int fr, int fq, LAS unsigned char* lds, int tid) const {
;     ...
; #pragma unroll
;         for (int bj = 0; bj < 2; ++bj) {
;             const unsigned colp = u.pn * 256 + bj * 128 + wc * 32 + 8 * fq;
;             const unsigned coll = bj * FF + u.pn * 128 + wc * 32 + 8 * fq;
; #pragma unroll
;             for (int n = 0; n < 2; ++n) {
;                 f32x4 c0 = ldf4(cw, coll + 4u * n), c1 = ldf4(cw, (unsigned)FF2 + coll + 4u * n), c2 = ldf4(cw, 2u * FF2 + coll + 4u * n);
;                 if constexpr (I8) { const f32x4 swv = ldf4(sw, colp + 4u * n); c0 = c0 * swv; c1 = c1 * swv; c2 = c2 * swv; }
;                 f32x4 hl = {0.f, 0.f, 0.f, 0.f}, hr = {0.f, 0.f, 0.f, 0.f};
;                 if (fr == 0 && lvalid) hl = ldf4(HALO, (2u * bk) * (unsigned)FF2 + colp + 4u * n);
;                 if (fr == 15 && rvalid) hr = ldf4(HALO, (2u * bk + 1u) * (unsigned)FF2 + colp + 4u * n);
; #pragma unroll
;                 for (int e = 0; e < 4; ++e) {
;                     const float prev = dpp_shr1(hl[e], acc[1][bj][3][n][e]);
;                     const float next = dpp_shl1(hr[e], acc[0][bj][0][n][e]);
;                     float left = prev;
; #pragma unroll
;                     for (int j = 0; j < 8; ++j) {
;                         const float cur = acc[j >> 2][bj][j & 3][n][e];
;                         const float nx = (j < 7) ? acc[(j + 1) >> 2][bj][(j + 1) & 3][n][e] : next;
;                         acc[j >> 2][bj][j & 3][n][e] = c0[e] * left + c1[e] * cur + c2[e] * nx;
;                         left = cur;
;                     }
;                 }
;                 asm volatile("" ::: "memory");
;             }
;         }
;         const unsigned colo = u.pn * 128 + wc * 32 + 8 * fq;
; #pragma unroll
;         for (int ai = 0; ai < 2; ++ai)
; #pragma unroll
;             for (int m = 0; m < 4; ++m) {
;                 f32x4 a[2];
; #pragma unroll
;                 for (int n = 0; n < 2; ++n)
; #pragma unroll
;                     for (int e = 0; e < 4; ++e) a[n][e] = silu_f(acc[ai][0][m][n][e]) * acc[ai][1][m][n][e];
;                 store_h8_nt((h16*)((char*)ACT + (((tok0 + tl0 + 4u * ai + m) * (unsigned)FF + colo) << 1)), a[0], a[1]);
;                 asm volatile("" ::: "memory");
;             }
	v_pk_mul_f32 v[82:83], v[30:31], v[20:21]
	v_pk_mul_f32 v[48:49], v[48:49], v[96:97]
	v_pk_fma_f32 v[54:55], v[54:55], v[18:19], v[82:83]
	v_pk_mul_f32 v[50:51], v[50:51], v[98:99]
	v_pk_fma_f32 v[54:55], v[26:27], v[22:23], v[54:55]
	v_cvt_pk_f16_f32 v48, v48, v49
	v_pk_mul_f32 v[54:55], v[72:73], v[54:55]
	v_pk_add_f32 v[72:73], v[80:81], 1.0 op_sel_hi:[1,0]
	v_rcp_f32_e32 v72, v72
	v_rcp_f32_e32 v73, v73
	v_pk_mul_f32 v[80:81], v[28:29], v[12:13]
	v_cvt_pk_f16_f32 v49, v50, v51
	v_pk_fma_f32 v[52:53], v[52:53], v[10:11], v[80:81]
	v_pk_mul_f32 v[72:73], v[74:75], v[72:73]
	v_pk_fma_f32 v[52:53], v[24:25], v[14:15], v[52:53]
	v_cvt_pk_f16_f32 v50, v54, v55
	v_pk_mul_f32 v[52:53], v[72:73], v[52:53]
	v_add_u32_e32 v72, 0x8400, v104
	v_cvt_pk_f16_f32 v51, v52, v53
	v_pk_mul_f32 v[52:53], v[44:45], s[100:101] op_sel_hi:[1,0]
	v_exp_f32_e32 v52, v52
	v_exp_f32_e32 v53, v53
	global_store_dwordx4 v72, v[48:51], s[14:15] nt
	v_pk_fma_f32 v[70:71], v[70:71], v[162:163], v[160:161]
	v_pk_mul_f32 v[160:161], v[62:63], v[192:193]
	v_pk_add_f32 v[48:49], v[52:53], 1.0 op_sel_hi:[1,0]
	v_pk_mul_f32 v[50:51], v[46:47], s[100:101] op_sel_hi:[1,0]
	v_rcp_f32_e32 v48, v48
	v_exp_f32_e32 v50, v50
	v_exp_f32_e32 v51, v51
	v_rcp_f32_e32 v49, v49
	v_pk_fma_f32 v[70:71], v[62:63], v[166:167], v[70:71]
	v_pk_add_f32 v[50:51], v[50:51], 1.0 op_sel_hi:[1,0]
	v_pk_mul_f32 v[44:45], v[44:45], v[48:49]
	v_pk_mul_f32 v[48:49], v[68:69], s[100:101] op_sel_hi:[1,0]
	v_rcp_f32_e32 v50, v50
	v_rcp_f32_e32 v51, v51
	v_exp_f32_e32 v48, v48
	v_exp_f32_e32 v49, v49
	v_pk_mul_f32 v[44:45], v[44:45], v[92:93]
	v_pk_mul_f32 v[46:47], v[46:47], v[50:51]
	v_pk_add_f32 v[48:49], v[48:49], 1.0 op_sel_hi:[1,0]
	v_pk_mul_f32 v[50:51], v[26:27], v[20:21]
	v_rcp_f32_e32 v48, v48
	v_rcp_f32_e32 v49, v49
	v_pk_fma_f32 v[30:31], v[30:31], v[18:19], v[50:51]
	v_pk_mul_f32 v[50:51], v[70:71], s[100:101] op_sel_hi:[1,0]
	v_exp_f32_e32 v50, v50
	v_exp_f32_e32 v51, v51
	v_pk_fma_f32 v[30:31], v[16:17], v[22:23], v[30:31]
	v_pk_mul_f32 v[48:49], v[68:69], v[48:49]
	v_pk_mul_f32 v[46:47], v[46:47], v[94:95]
	v_pk_mul_f32 v[30:31], v[48:49], v[30:31]
	v_pk_add_f32 v[48:49], v[50:51], 1.0 op_sel_hi:[1,0]
	v_rcp_f32_e32 v48, v48
	v_rcp_f32_e32 v49, v49
	v_pk_mul_f32 v[50:51], v[24:25], v[12:13]
	v_cvt_pk_f16_f32 v30, v30, v31
	v_pk_fma_f32 v[28:29], v[28:29], v[10:11], v[50:51]
	v_pk_mul_f32 v[48:49], v[70:71], v[48:49]
	v_pk_fma_f32 v[28:29], v[8:9], v[14:15], v[28:29]
	v_add_u32_e32 v50, 0xb000, v104
	v_pk_mul_f32 v[48:49], v[48:49], v[28:29]
	v_cvt_pk_f16_f32 v28, v44, v45
	v_pk_mul_f32 v[44:45], v[40:41], s[100:101] op_sel_hi:[1,0]
	v_exp_f32_e32 v44, v44
	v_exp_f32_e32 v45, v45
	v_cvt_pk_f16_f32 v29, v46, v47
	v_cvt_pk_f16_f32 v31, v48, v49
	global_store_dwordx4 v50, v[28:31], s[14:15] nt
	v_pk_fma_f32 v[66:67], v[66:67], v[162:163], v[160:161]
	v_pk_fma_f32 v[90:91], v[78:79], v[194:195], v[90:91]
	v_pk_add_f32 v[28:29], v[44:45], 1.0 op_sel_hi:[1,0]
	v_pk_mul_f32 v[30:31], v[42:43], s[100:101] op_sel_hi:[1,0]
	v_rcp_f32_e32 v28, v28
	v_exp_f32_e32 v30, v30
	v_exp_f32_e32 v31, v31
	v_rcp_f32_e32 v29, v29
	v_pk_fma_f32 v[66:67], v[58:59], v[166:167], v[66:67]
	v_pk_add_f32 v[30:31], v[30:31], 1.0 op_sel_hi:[1,0]
	v_pk_mul_f32 v[28:29], v[40:41], v[28:29]
	v_pk_mul_f32 v[40:41], v[64:65], s[100:101] op_sel_hi:[1,0]
	v_rcp_f32_e32 v30, v30
	v_rcp_f32_e32 v31, v31
	v_exp_f32_e32 v40, v40
	v_exp_f32_e32 v41, v41
	v_pk_mul_f32 v[28:29], v[28:29], v[88:89]
	v_pk_mul_f32 v[30:31], v[42:43], v[30:31]
	v_pk_add_f32 v[40:41], v[40:41], 1.0 op_sel_hi:[1,0]
	v_pk_mul_f32 v[42:43], v[16:17], v[20:21]
	v_rcp_f32_e32 v40, v40
	v_rcp_f32_e32 v41, v41
	v_pk_fma_f32 v[26:27], v[26:27], v[18:19], v[42:43]
	v_pk_mul_f32 v[42:43], v[66:67], s[100:101] op_sel_hi:[1,0]
	v_exp_f32_e32 v42, v42
	v_exp_f32_e32 v43, v43
	v_pk_fma_f32 v[26:27], v[2:3], v[22:23], v[26:27]
	v_pk_mul_f32 v[40:41], v[64:65], v[40:41]
	v_pk_mul_f32 v[30:31], v[30:31], v[90:91]
	v_pk_mul_f32 v[26:27], v[40:41], v[26:27]
	v_pk_add_f32 v[40:41], v[42:43], 1.0 op_sel_hi:[1,0]
	v_rcp_f32_e32 v40, v40
	v_rcp_f32_e32 v41, v41
	v_pk_mul_f32 v[42:43], v[8:9], v[12:13]
	v_pk_fma_f32 v[60:61], v[234:235], v[164:165], v[60:61]
	v_pk_fma_f32 v[24:25], v[24:25], v[10:11], v[42:43]
	v_pk_mul_f32 v[40:41], v[66:67], v[40:41]
	v_pk_fma_f32 v[24:25], v[4:5], v[14:15], v[24:25]
	v_add_u32_e32 v42, 0xdc00, v104
	v_pk_mul_f32 v[40:41], v[40:41], v[24:25]
; #define PG8_BAR __builtin_amdgcn_s_barrier()
; __device__ __forceinline__ float silu_f(float x) { return x * __builtin_amdgcn_rcpf(1.0f + __expf(-x)); }
; template <class Prob, class Epi, bool I8 = false, bool ALIGN_EPI = true, bool SP2 = true>
; __device__ __forceinline__ void gemm_phase(LAS unsigned char* lds, int wave, const Prob& P, const Epi& E) {
;     ...
;         if (!has_next) break;
;         if (!cur.keep) {
; #pragma unroll
;         for (int a = 0; a < 2; ++a)
; #pragma unroll
;             for (int b = 0; b < 2; ++b)
; #pragma unroll
;                 for (int m = 0; m < 4; ++m)
; #pragma unroll
;                     for (int n = 0; n < 2; ++n) acc[a][b][m][n] = (f32x4){0.f, 0.f, 0.f, 0.f};
;         }
;         cur = nxt; cA = nA; cB = nB; ++ui;
;         if constexpr (ALIGN_EPI) { if (wr == 1) PG8_BAR; }
;     __device__ __forceinline__ void operator()(Acc& acc, const Unit& u, int wr, int wc, int fr, int fq, LAS unsigned char* lds, int tid) const {
;     ...
;         const unsigned colo = u.pn * 128 + wc * 32 + 8 * fq;
; #pragma unroll
;         for (int ai = 0; ai < 2; ++ai)
; #pragma unroll
;             for (int m = 0; m < 4; ++m) {
;                 f32x4 a[2];
; #pragma unroll
;                 for (int n = 0; n < 2; ++n)
; #pragma unroll
;                     for (int e = 0; e < 4; ++e) a[n][e] = silu_f(acc[ai][0][m][n][e]) * acc[ai][1][m][n][e];
;                 store_h8_nt((h16*)((char*)ACT + (((tok0 + tl0 + 4u * ai + m) * (unsigned)FF + colo) << 1)), a[0], a[1]);
;                 asm volatile("" ::: "memory");
;             }
	v_cvt_pk_f16_f32 v24, v28, v29
	v_pk_mul_f32 v[28:29], v[36:37], s[100:101] op_sel_hi:[1,0]
	v_exp_f32_e32 v28, v28
	v_exp_f32_e32 v29, v29
	v_cvt_pk_f16_f32 v25, v30, v31
	v_cvt_pk_f16_f32 v26, v26, v27
	v_cvt_pk_f16_f32 v27, v40, v41
	global_store_dwordx4 v42, v[24:27], s[14:15] nt
	v_pk_mul_f32 v[160:161], v[58:59], v[192:193]
	v_pk_mul_f32 v[30:31], v[2:3], v[20:21]
	v_pk_add_f32 v[24:25], v[28:29], 1.0 op_sel_hi:[1,0]
	v_pk_mul_f32 v[28:29], v[60:61], s[100:101] op_sel_hi:[1,0]
	v_exp_f32_e32 v28, v28
	v_exp_f32_e32 v29, v29
	v_pk_fma_f32 v[62:63], v[62:63], v[162:163], v[160:161]
	v_pk_fma_f32 v[62:63], v[230:231], v[166:167], v[62:63]
	v_pk_add_f32 v[28:29], v[28:29], 1.0 op_sel_hi:[1,0]
	v_pk_mul_f32 v[26:27], v[38:39], s[100:101] op_sel_hi:[1,0]
	v_rcp_f32_e32 v28, v28
	v_rcp_f32_e32 v29, v29
	v_pk_fma_f32 v[16:17], v[16:17], v[18:19], v[30:31]
	v_pk_mul_f32 v[30:31], v[62:63], s[100:101] op_sel_hi:[1,0]
	v_exp_f32_e32 v26, v26
	v_exp_f32_e32 v27, v27
	v_exp_f32_e32 v30, v30
	v_exp_f32_e32 v31, v31
	v_pk_fma_f32 v[16:17], v[6:7], v[22:23], v[16:17]
	v_pk_mul_f32 v[28:29], v[60:61], v[28:29]
	v_pk_add_f32 v[26:27], v[26:27], 1.0 op_sel_hi:[1,0]
	v_pk_mul_f32 v[16:17], v[28:29], v[16:17]
	v_pk_add_f32 v[28:29], v[30:31], 1.0 op_sel_hi:[1,0]
	v_rcp_f32_e32 v24, v24
	v_rcp_f32_e32 v25, v25
	v_rcp_f32_e32 v26, v26
	v_rcp_f32_e32 v27, v27
	v_rcp_f32_e32 v28, v28
	v_rcp_f32_e32 v29, v29
	v_pk_mul_f32 v[30:31], v[4:5], v[12:13]
	v_pk_fma_f32 v[86:87], v[238:239], v[194:195], v[86:87]
	v_pk_fma_f32 v[8:9], v[8:9], v[10:11], v[30:31]
	v_pk_mul_f32 v[24:25], v[36:37], v[24:25]
	v_pk_mul_f32 v[26:27], v[38:39], v[26:27]
	v_pk_fma_f32 v[8:9], v[0:1], v[14:15], v[8:9]
	v_pk_mul_f32 v[28:29], v[62:63], v[28:29]
	v_pk_mul_f32 v[24:25], v[24:25], v[84:85]
	v_pk_mul_f32 v[26:27], v[26:27], v[86:87]
	v_pk_mul_f32 v[8:9], v[28:29], v[8:9]
	v_pk_fma_f32 v[56:57], v[164:165], v[172:173], v[56:57]
	v_add_u32_e32 v28, 0x10800, v104
	v_cvt_pk_f16_f32 v24, v24, v25
	v_cvt_pk_f16_f32 v25, v26, v27
	v_cvt_pk_f16_f32 v26, v16, v17
	v_cvt_pk_f16_f32 v27, v8, v9
	global_store_dwordx4 v28, v[24:27], s[14:15] nt
	v_pk_mul_f32 v[58:59], v[58:59], v[162:163]
	s_nop 0
	v_pk_mul_f32 v[24:25], v[56:57], s[100:101] op_sel_hi:[1,0]
	v_exp_f32_e32 v24, v24
	v_exp_f32_e32 v25, v25
	v_pk_fma_f32 v[58:59], v[230:231], v[192:193], v[58:59]
	v_pk_mul_f32 v[8:9], v[32:33], s[100:101] op_sel_hi:[1,0]
	v_pk_fma_f32 v[58:59], v[166:167], v[174:175], v[58:59]
	v_pk_add_f32 v[24:25], v[24:25], 1.0 op_sel_hi:[1,0]
	v_pk_mul_f32 v[16:17], v[34:35], s[100:101] op_sel_hi:[1,0]
	v_rcp_f32_e32 v24, v24
	v_rcp_f32_e32 v25, v25
	v_pk_mul_f32 v[2:3], v[2:3], v[18:19]
	v_pk_mul_f32 v[18:19], v[58:59], s[100:101] op_sel_hi:[1,0]
	v_exp_f32_e32 v8, v8
	v_exp_f32_e32 v9, v9
	v_exp_f32_e32 v16, v16
	v_exp_f32_e32 v17, v17
	v_exp_f32_e32 v18, v18
	v_exp_f32_e32 v19, v19
	v_mov_b32_dpp v108, v134 row_shl:1 row_mask:0xf bank_mask:0xf
	v_mov_b32_dpp v109, v135 row_shl:1 row_mask:0xf bank_mask:0xf
	v_pk_fma_f32 v[2:3], v[6:7], v[20:21], v[2:3]
	v_pk_mul_f32 v[6:7], v[56:57], v[24:25]
	v_pk_fma_f32 v[2:3], v[22:23], v[108:109], v[2:3]
	v_pk_add_f32 v[8:9], v[8:9], 1.0 op_sel_hi:[1,0]
	v_pk_add_f32 v[16:17], v[16:17], 1.0 op_sel_hi:[1,0]
	v_pk_mul_f32 v[2:3], v[6:7], v[2:3]
	v_pk_add_f32 v[6:7], v[18:19], 1.0 op_sel_hi:[1,0]
	v_rcp_f32_e32 v8, v8
	v_rcp_f32_e32 v9, v9
	v_rcp_f32_e32 v16, v16
	v_rcp_f32_e32 v17, v17
	v_rcp_f32_e32 v6, v6
	v_rcp_f32_e32 v7, v7
	v_pk_mul_f32 v[78:79], v[78:79], v[214:215]
	v_pk_mul_f32 v[4:5], v[4:5], v[10:11]
	v_pk_fma_f32 v[78:79], v[238:239], v[198:199], v[78:79]
	v_pk_fma_f32 v[0:1], v[0:1], v[12:13], v[4:5]
	v_pk_fma_f32 v[78:79], v[194:195], v[206:207], v[78:79]
	v_pk_mul_f32 v[8:9], v[32:33], v[8:9]
	v_pk_mul_f32 v[16:17], v[34:35], v[16:17]
	v_pk_fma_f32 v[0:1], v[14:15], v[110:111], v[0:1]
	v_pk_mul_f32 v[4:5], v[58:59], v[6:7]
	v_pk_mul_f32 v[8:9], v[8:9], v[76:77]
	v_pk_mul_f32 v[16:17], v[16:17], v[78:79]
	v_pk_mul_f32 v[4:5], v[4:5], v[0:1]
	v_add_u32_e32 v6, 0x13400, v104
	v_cvt_pk_f16_f32 v0, v8, v9
	v_cvt_pk_f16_f32 v1, v16, v17
	v_cvt_pk_f16_f32 v2, v2, v3
	v_cvt_pk_f16_f32 v3, v4, v5
	global_store_dwordx4 v6, v[0:3], s[14:15] nt
	s_cmp_eq_u32 s101, 0
	s_cbranch_scc1 .Lh1065_exit
	s_cmp_eq_u64 s[16:17], 0
	s_cbranch_scc1 .Lpeel_1065
	s_barrier
	s_branch .Lpeel_1065
.Lh1065_exit:
	s_mov_b64 s[36:37], -1
	s_mov_b64 vcc, 0
	s_branch .LBB0_1087
